# M3: conv+silu of q/k rows hand-written on natural channel pairs (packed mul/add, same summation order, no shuffles)
# speedup vs baseline: 1.0053x; 1.0040x over previous
.LBB0_721:
	s_or_b64 exec, exec, s[0:1]
	v_lshlrev_b32_e32 v2, 3, v157
	s_lshl_b32 s4, s59, 2
	v_and_b32_e32 v156, 0x78, v2
	s_add_i32 s0, s4, 0
	v_lshl_add_u32 v198, v156, 2, s0
	v_ashrrev_i32_e32 v160, 3, v157
	v_and_b32_e32 v159, -2, v160
	v_lshlrev_b32_e32 v2, 1, v156
	v_mad_u32_u24 v124, v159, s48, v2
	v_add_u32_e32 v125, 0x110, v124
	s_mov_b32 s0, 0xbfb8aa3b
	s_mov_b32 vcc_lo, 0x3db504f3
	v_add_u32_e32 v3, 0x19000, v198
	ds_read_b128 v[162:165], v3
	ds_read_b128 v[166:169], v3 offset:4096
	ds_read_b128 v[170:173], v3 offset:8192
	ds_read_b128 v[174:177], v3 offset:12288
	v_lshlrev_b32_e32 v178, 16, v92
	v_and_b32_e32 v179, 0xffff0000, v92
	v_lshlrev_b32_e32 v180, 16, v93
	v_and_b32_e32 v181, 0xffff0000, v93
	v_lshlrev_b32_e32 v182, 16, v88
	v_and_b32_e32 v183, 0xffff0000, v88
	v_lshlrev_b32_e32 v184, 16, v89
	v_and_b32_e32 v185, 0xffff0000, v89
	v_lshlrev_b32_e32 v186, 16, v96
	v_and_b32_e32 v187, 0xffff0000, v96
	v_lshlrev_b32_e32 v188, 16, v97
	v_and_b32_e32 v189, 0xffff0000, v97
	v_lshlrev_b32_e32 v190, 16, v100
	v_and_b32_e32 v191, 0xffff0000, v100
	v_lshlrev_b32_e32 v192, 16, v101
	v_and_b32_e32 v193, 0xffff0000, v101
	v_lshlrev_b32_e32 v194, 16, v104
	v_and_b32_e32 v195, 0xffff0000, v104
	v_lshlrev_b32_e32 v196, 16, v105
	v_and_b32_e32 v197, 0xffff0000, v105
	s_waitcnt lgkmcnt(0)
	v_pk_mul_f32 v[108:109], v[162:163], v[178:179]
	v_pk_mul_f32 v[110:111], v[164:165], v[180:181]
	v_pk_mul_f32 v[112:113], v[162:163], v[182:183]
	v_pk_mul_f32 v[114:115], v[164:165], v[184:185]
	v_pk_mul_f32 v[116:117], v[166:167], v[182:183]
	v_pk_mul_f32 v[118:119], v[168:169], v[184:185]
	v_pk_mul_f32 v[120:121], v[166:167], v[186:187]
	v_pk_mul_f32 v[122:123], v[168:169], v[188:189]
	v_pk_add_f32 v[108:109], v[116:117], v[108:109]
	v_pk_add_f32 v[110:111], v[118:119], v[110:111]
	v_pk_add_f32 v[112:113], v[120:121], v[112:113]
	v_pk_add_f32 v[114:115], v[122:123], v[114:115]
	v_pk_mul_f32 v[116:117], v[170:171], v[186:187]
	v_pk_mul_f32 v[118:119], v[172:173], v[188:189]
	v_pk_mul_f32 v[120:121], v[170:171], v[190:191]
	v_pk_mul_f32 v[122:123], v[172:173], v[192:193]
	v_pk_add_f32 v[108:109], v[116:117], v[108:109]
	v_pk_add_f32 v[110:111], v[118:119], v[110:111]
	v_pk_add_f32 v[112:113], v[120:121], v[112:113]
	v_pk_add_f32 v[114:115], v[122:123], v[114:115]
	v_pk_mul_f32 v[116:117], v[174:175], v[190:191]
	v_pk_mul_f32 v[118:119], v[176:177], v[192:193]
	v_pk_mul_f32 v[120:121], v[174:175], v[194:195]
	v_pk_mul_f32 v[122:123], v[176:177], v[196:197]
	v_pk_add_f32 v[108:109], v[116:117], v[108:109]
	v_pk_add_f32 v[110:111], v[118:119], v[110:111]
	v_pk_add_f32 v[112:113], v[120:121], v[112:113]
	v_pk_add_f32 v[114:115], v[122:123], v[114:115]
	v_pk_mul_f32 v[116:117], v[108:109], s[0:1] op_sel_hi:[1,0]
	v_pk_mul_f32 v[118:119], v[110:111], s[0:1] op_sel_hi:[1,0]
	v_pk_mul_f32 v[120:121], v[112:113], s[0:1] op_sel_hi:[1,0]
	v_pk_mul_f32 v[122:123], v[114:115], s[0:1] op_sel_hi:[1,0]
	v_exp_f32_e32 v116, v116
	v_exp_f32_e32 v117, v117
	v_exp_f32_e32 v118, v118
	v_exp_f32_e32 v119, v119
	v_exp_f32_e32 v120, v120
	v_exp_f32_e32 v121, v121
	v_exp_f32_e32 v122, v122
	v_exp_f32_e32 v123, v123
	v_pk_add_f32 v[116:117], v[116:117], 1.0 op_sel_hi:[1,0]
	v_pk_add_f32 v[118:119], v[118:119], 1.0 op_sel_hi:[1,0]
	v_pk_add_f32 v[120:121], v[120:121], 1.0 op_sel_hi:[1,0]
	v_pk_add_f32 v[122:123], v[122:123], 1.0 op_sel_hi:[1,0]
	v_rcp_f32_e32 v116, v116
	v_rcp_f32_e32 v117, v117
	v_rcp_f32_e32 v118, v118
	v_rcp_f32_e32 v119, v119
	v_rcp_f32_e32 v120, v120
	v_rcp_f32_e32 v121, v121
	v_rcp_f32_e32 v122, v122
	v_rcp_f32_e32 v123, v123
	v_pk_mul_f32 v[92:93], v[108:109], v[116:117]
	v_pk_mul_f32 v[88:89], v[110:111], v[118:119]
	v_pk_mul_f32 v[96:97], v[112:113], v[120:121]
	v_pk_mul_f32 v[100:101], v[114:115], v[122:123]
	ds_read_b128 v[162:165], v3 offset:16
	ds_read_b128 v[166:169], v3 offset:4112
	ds_read_b128 v[170:173], v3 offset:8208
	ds_read_b128 v[174:177], v3 offset:12304
	v_lshlrev_b32_e32 v178, 16, v94
	v_and_b32_e32 v179, 0xffff0000, v94
	v_lshlrev_b32_e32 v180, 16, v95
	v_and_b32_e32 v181, 0xffff0000, v95
	v_lshlrev_b32_e32 v182, 16, v90
	v_and_b32_e32 v183, 0xffff0000, v90
	v_lshlrev_b32_e32 v184, 16, v91
	v_and_b32_e32 v185, 0xffff0000, v91
	v_lshlrev_b32_e32 v186, 16, v98
	v_and_b32_e32 v187, 0xffff0000, v98
	v_lshlrev_b32_e32 v188, 16, v99
	v_and_b32_e32 v189, 0xffff0000, v99
	v_lshlrev_b32_e32 v190, 16, v102
	v_and_b32_e32 v191, 0xffff0000, v102
	v_lshlrev_b32_e32 v192, 16, v103
	v_and_b32_e32 v193, 0xffff0000, v103
	v_lshlrev_b32_e32 v194, 16, v106
	v_and_b32_e32 v195, 0xffff0000, v106
	v_lshlrev_b32_e32 v196, 16, v107
	v_and_b32_e32 v197, 0xffff0000, v107
	s_waitcnt lgkmcnt(0)
	v_pk_mul_f32 v[108:109], v[162:163], v[178:179]
	v_pk_mul_f32 v[110:111], v[164:165], v[180:181]
	v_pk_mul_f32 v[112:113], v[162:163], v[182:183]
	v_pk_mul_f32 v[114:115], v[164:165], v[184:185]
	v_pk_mul_f32 v[116:117], v[166:167], v[182:183]
	v_pk_mul_f32 v[118:119], v[168:169], v[184:185]
	v_pk_mul_f32 v[120:121], v[166:167], v[186:187]
	v_pk_mul_f32 v[122:123], v[168:169], v[188:189]
	v_pk_add_f32 v[108:109], v[116:117], v[108:109]
	v_pk_add_f32 v[110:111], v[118:119], v[110:111]
	v_pk_add_f32 v[112:113], v[120:121], v[112:113]
	v_pk_add_f32 v[114:115], v[122:123], v[114:115]
	v_pk_mul_f32 v[116:117], v[170:171], v[186:187]
	v_pk_mul_f32 v[118:119], v[172:173], v[188:189]
	v_pk_mul_f32 v[120:121], v[170:171], v[190:191]
	v_pk_mul_f32 v[122:123], v[172:173], v[192:193]
	v_pk_add_f32 v[108:109], v[116:117], v[108:109]
	v_pk_add_f32 v[110:111], v[118:119], v[110:111]
	v_pk_add_f32 v[112:113], v[120:121], v[112:113]
	v_pk_add_f32 v[114:115], v[122:123], v[114:115]
	v_pk_mul_f32 v[116:117], v[174:175], v[190:191]
	v_pk_mul_f32 v[118:119], v[176:177], v[192:193]
	v_pk_mul_f32 v[120:121], v[174:175], v[194:195]
	v_pk_mul_f32 v[122:123], v[176:177], v[196:197]
	v_pk_add_f32 v[108:109], v[116:117], v[108:109]
	v_pk_add_f32 v[110:111], v[118:119], v[110:111]
	v_pk_add_f32 v[112:113], v[120:121], v[112:113]
	v_pk_add_f32 v[114:115], v[122:123], v[114:115]
	v_pk_mul_f32 v[116:117], v[108:109], s[0:1] op_sel_hi:[1,0]
	v_pk_mul_f32 v[118:119], v[110:111], s[0:1] op_sel_hi:[1,0]
	v_pk_mul_f32 v[120:121], v[112:113], s[0:1] op_sel_hi:[1,0]
	v_pk_mul_f32 v[122:123], v[114:115], s[0:1] op_sel_hi:[1,0]
	v_exp_f32_e32 v116, v116
	v_exp_f32_e32 v117, v117
	v_exp_f32_e32 v118, v118
	v_exp_f32_e32 v119, v119
	v_exp_f32_e32 v120, v120
	v_exp_f32_e32 v121, v121
	v_exp_f32_e32 v122, v122
	v_exp_f32_e32 v123, v123
	v_pk_add_f32 v[116:117], v[116:117], 1.0 op_sel_hi:[1,0]
	v_pk_add_f32 v[118:119], v[118:119], 1.0 op_sel_hi:[1,0]
	v_pk_add_f32 v[120:121], v[120:121], 1.0 op_sel_hi:[1,0]
	v_pk_add_f32 v[122:123], v[122:123], 1.0 op_sel_hi:[1,0]
	v_rcp_f32_e32 v116, v116
	v_rcp_f32_e32 v117, v117
	v_rcp_f32_e32 v118, v118
	v_rcp_f32_e32 v119, v119
	v_rcp_f32_e32 v120, v120
	v_rcp_f32_e32 v121, v121
	v_rcp_f32_e32 v122, v122
	v_rcp_f32_e32 v123, v123
	v_pk_mul_f32 v[108:109], v[108:109], v[116:117]
	v_pk_mul_f32 v[110:111], v[110:111], v[118:119]
	v_pk_mul_f32 v[112:113], v[112:113], v[120:121]
	v_pk_mul_f32 v[114:115], v[114:115], v[122:123]
	v_cvt_pk_bf16_f32 v116, v92, v93
	v_cvt_pk_bf16_f32 v117, v88, v89
	v_cvt_pk_bf16_f32 v118, v108, v109
	v_cvt_pk_bf16_f32 v119, v110, v111
	v_cvt_pk_bf16_f32 v120, v96, v97
	v_cvt_pk_bf16_f32 v121, v100, v101
	v_cvt_pk_bf16_f32 v122, v112, v113
	v_cvt_pk_bf16_f32 v123, v114, v115
	ds_write_b128 v124, v[116:119]
	ds_write_b128 v125, v[120:123]
	v_add_u32_e32 v3, 0x19800, v198
	ds_read_b128 v[162:165], v3
	ds_read_b128 v[166:169], v3 offset:4096
	ds_read_b128 v[170:173], v3 offset:8192
	ds_read_b128 v[174:177], v3 offset:12288
	v_lshlrev_b32_e32 v178, 16, v68
	v_and_b32_e32 v179, 0xffff0000, v68
	v_lshlrev_b32_e32 v180, 16, v69
	v_and_b32_e32 v181, 0xffff0000, v69
	v_lshlrev_b32_e32 v182, 16, v76
	v_and_b32_e32 v183, 0xffff0000, v76
	v_lshlrev_b32_e32 v184, 16, v77
	v_and_b32_e32 v185, 0xffff0000, v77
	v_lshlrev_b32_e32 v186, 16, v72
	v_and_b32_e32 v187, 0xffff0000, v72
	v_lshlrev_b32_e32 v188, 16, v73
	v_and_b32_e32 v189, 0xffff0000, v73
	v_lshlrev_b32_e32 v190, 16, v80
	v_and_b32_e32 v191, 0xffff0000, v80
	v_lshlrev_b32_e32 v192, 16, v81
	v_and_b32_e32 v193, 0xffff0000, v81
	v_lshlrev_b32_e32 v194, 16, v84
	v_and_b32_e32 v195, 0xffff0000, v84
	v_lshlrev_b32_e32 v196, 16, v85
	v_and_b32_e32 v197, 0xffff0000, v85
	s_waitcnt lgkmcnt(0)
	v_pk_mul_f32 v[108:109], v[162:163], v[178:179]
	v_pk_mul_f32 v[110:111], v[164:165], v[180:181]
	v_pk_mul_f32 v[112:113], v[162:163], v[182:183]
	v_pk_mul_f32 v[114:115], v[164:165], v[184:185]
	v_pk_mul_f32 v[116:117], v[166:167], v[182:183]
	v_pk_mul_f32 v[118:119], v[168:169], v[184:185]
	v_pk_mul_f32 v[120:121], v[166:167], v[186:187]
	v_pk_mul_f32 v[122:123], v[168:169], v[188:189]
	v_pk_add_f32 v[108:109], v[116:117], v[108:109]
	v_pk_add_f32 v[110:111], v[118:119], v[110:111]
	v_pk_add_f32 v[112:113], v[120:121], v[112:113]
	v_pk_add_f32 v[114:115], v[122:123], v[114:115]
	v_pk_mul_f32 v[116:117], v[170:171], v[186:187]
	v_pk_mul_f32 v[118:119], v[172:173], v[188:189]
	v_pk_mul_f32 v[120:121], v[170:171], v[190:191]
	v_pk_mul_f32 v[122:123], v[172:173], v[192:193]
	v_pk_add_f32 v[108:109], v[116:117], v[108:109]
	v_pk_add_f32 v[110:111], v[118:119], v[110:111]
	v_pk_add_f32 v[112:113], v[120:121], v[112:113]
	v_pk_add_f32 v[114:115], v[122:123], v[114:115]
	v_pk_mul_f32 v[116:117], v[174:175], v[190:191]
	v_pk_mul_f32 v[118:119], v[176:177], v[192:193]
	v_pk_mul_f32 v[120:121], v[174:175], v[194:195]
	v_pk_mul_f32 v[122:123], v[176:177], v[196:197]
	v_pk_add_f32 v[108:109], v[116:117], v[108:109]
	v_pk_add_f32 v[110:111], v[118:119], v[110:111]
	v_pk_add_f32 v[112:113], v[120:121], v[112:113]
	v_pk_add_f32 v[114:115], v[122:123], v[114:115]
	v_pk_mul_f32 v[116:117], v[108:109], s[0:1] op_sel_hi:[1,0]
	v_pk_mul_f32 v[118:119], v[110:111], s[0:1] op_sel_hi:[1,0]
	v_pk_mul_f32 v[120:121], v[112:113], s[0:1] op_sel_hi:[1,0]
	v_pk_mul_f32 v[122:123], v[114:115], s[0:1] op_sel_hi:[1,0]
	v_exp_f32_e32 v116, v116
	v_exp_f32_e32 v117, v117
	v_exp_f32_e32 v118, v118
	v_exp_f32_e32 v119, v119
	v_exp_f32_e32 v120, v120
	v_exp_f32_e32 v121, v121
	v_exp_f32_e32 v122, v122
	v_exp_f32_e32 v123, v123
	v_pk_add_f32 v[116:117], v[116:117], 1.0 op_sel_hi:[1,0]
	v_pk_add_f32 v[118:119], v[118:119], 1.0 op_sel_hi:[1,0]
	v_pk_add_f32 v[120:121], v[120:121], 1.0 op_sel_hi:[1,0]
	v_pk_add_f32 v[122:123], v[122:123], 1.0 op_sel_hi:[1,0]
	v_rcp_f32_e32 v116, v116
	v_rcp_f32_e32 v117, v117
	v_rcp_f32_e32 v118, v118
	v_rcp_f32_e32 v119, v119
	v_rcp_f32_e32 v120, v120
	v_rcp_f32_e32 v121, v121
	v_rcp_f32_e32 v122, v122
	v_rcp_f32_e32 v123, v123
	v_pk_mul_f32 v[68:69], v[108:109], v[116:117]
	v_pk_mul_f32 v[76:77], v[110:111], v[118:119]
	v_pk_mul_f32 v[72:73], v[112:113], v[120:121]
	v_pk_mul_f32 v[80:81], v[114:115], v[122:123]
	ds_read_b128 v[162:165], v3 offset:16
	ds_read_b128 v[166:169], v3 offset:4112
	ds_read_b128 v[170:173], v3 offset:8208
	ds_read_b128 v[174:177], v3 offset:12304
	v_lshlrev_b32_e32 v178, 16, v70
	v_and_b32_e32 v179, 0xffff0000, v70
	v_lshlrev_b32_e32 v180, 16, v71
	v_and_b32_e32 v181, 0xffff0000, v71
	v_lshlrev_b32_e32 v182, 16, v78
	v_and_b32_e32 v183, 0xffff0000, v78
	v_lshlrev_b32_e32 v184, 16, v79
	v_and_b32_e32 v185, 0xffff0000, v79
	v_lshlrev_b32_e32 v186, 16, v74
	v_and_b32_e32 v187, 0xffff0000, v74
	v_lshlrev_b32_e32 v188, 16, v75
	v_and_b32_e32 v189, 0xffff0000, v75
	v_lshlrev_b32_e32 v190, 16, v82
	v_and_b32_e32 v191, 0xffff0000, v82
	v_lshlrev_b32_e32 v192, 16, v83
	v_and_b32_e32 v193, 0xffff0000, v83
	v_lshlrev_b32_e32 v194, 16, v86
	v_and_b32_e32 v195, 0xffff0000, v86
	v_lshlrev_b32_e32 v196, 16, v87
	v_and_b32_e32 v197, 0xffff0000, v87
	s_waitcnt lgkmcnt(0)
	v_pk_mul_f32 v[108:109], v[162:163], v[178:179]
	v_pk_mul_f32 v[110:111], v[164:165], v[180:181]
	v_pk_mul_f32 v[112:113], v[162:163], v[182:183]
	v_pk_mul_f32 v[114:115], v[164:165], v[184:185]
	v_pk_mul_f32 v[116:117], v[166:167], v[182:183]
	v_pk_mul_f32 v[118:119], v[168:169], v[184:185]
	v_pk_mul_f32 v[120:121], v[166:167], v[186:187]
	v_pk_mul_f32 v[122:123], v[168:169], v[188:189]
	v_pk_add_f32 v[108:109], v[116:117], v[108:109]
	v_pk_add_f32 v[110:111], v[118:119], v[110:111]
	v_pk_add_f32 v[112:113], v[120:121], v[112:113]
	v_pk_add_f32 v[114:115], v[122:123], v[114:115]
	v_pk_mul_f32 v[116:117], v[170:171], v[186:187]
	v_pk_mul_f32 v[118:119], v[172:173], v[188:189]
	v_pk_mul_f32 v[120:121], v[170:171], v[190:191]
	v_pk_mul_f32 v[122:123], v[172:173], v[192:193]
	v_pk_add_f32 v[108:109], v[116:117], v[108:109]
	v_pk_add_f32 v[110:111], v[118:119], v[110:111]
	v_pk_add_f32 v[112:113], v[120:121], v[112:113]
	v_pk_add_f32 v[114:115], v[122:123], v[114:115]
	v_pk_mul_f32 v[116:117], v[174:175], v[190:191]
	v_pk_mul_f32 v[118:119], v[176:177], v[192:193]
	v_pk_mul_f32 v[120:121], v[174:175], v[194:195]
	v_pk_mul_f32 v[122:123], v[176:177], v[196:197]
	v_pk_add_f32 v[108:109], v[116:117], v[108:109]
	v_pk_add_f32 v[110:111], v[118:119], v[110:111]
	v_pk_add_f32 v[112:113], v[120:121], v[112:113]
	v_pk_add_f32 v[114:115], v[122:123], v[114:115]
	v_pk_mul_f32 v[116:117], v[108:109], s[0:1] op_sel_hi:[1,0]
	v_pk_mul_f32 v[118:119], v[110:111], s[0:1] op_sel_hi:[1,0]
	v_pk_mul_f32 v[120:121], v[112:113], s[0:1] op_sel_hi:[1,0]
	v_pk_mul_f32 v[122:123], v[114:115], s[0:1] op_sel_hi:[1,0]
	v_exp_f32_e32 v116, v116
	v_exp_f32_e32 v117, v117
	v_exp_f32_e32 v118, v118
	v_exp_f32_e32 v119, v119
	v_exp_f32_e32 v120, v120
	v_exp_f32_e32 v121, v121
	v_exp_f32_e32 v122, v122
	v_exp_f32_e32 v123, v123
	v_pk_add_f32 v[116:117], v[116:117], 1.0 op_sel_hi:[1,0]
	v_pk_add_f32 v[118:119], v[118:119], 1.0 op_sel_hi:[1,0]
	v_pk_add_f32 v[120:121], v[120:121], 1.0 op_sel_hi:[1,0]
	v_pk_add_f32 v[122:123], v[122:123], 1.0 op_sel_hi:[1,0]
	v_rcp_f32_e32 v116, v116
	v_rcp_f32_e32 v117, v117
	v_rcp_f32_e32 v118, v118
	v_rcp_f32_e32 v119, v119
	v_rcp_f32_e32 v120, v120
	v_rcp_f32_e32 v121, v121
	v_rcp_f32_e32 v122, v122
	v_rcp_f32_e32 v123, v123
	v_pk_mul_f32 v[108:109], v[108:109], v[116:117]
	v_pk_mul_f32 v[110:111], v[110:111], v[118:119]
	v_pk_mul_f32 v[112:113], v[112:113], v[120:121]
	v_pk_mul_f32 v[114:115], v[114:115], v[122:123]
	v_pk_mul_f32 v[68:69], v[68:69], vcc op_sel_hi:[1,0]
	v_pk_mul_f32 v[76:77], v[76:77], vcc op_sel_hi:[1,0]
	v_pk_mul_f32 v[72:73], v[72:73], vcc op_sel_hi:[1,0]
	v_pk_mul_f32 v[80:81], v[80:81], vcc op_sel_hi:[1,0]
	v_pk_mul_f32 v[108:109], v[108:109], vcc op_sel_hi:[1,0]
	v_pk_mul_f32 v[110:111], v[110:111], vcc op_sel_hi:[1,0]
	v_pk_mul_f32 v[112:113], v[112:113], vcc op_sel_hi:[1,0]
	v_pk_mul_f32 v[114:115], v[114:115], vcc op_sel_hi:[1,0]
	v_cvt_pk_bf16_f32 v116, v68, v69
	v_cvt_pk_bf16_f32 v117, v76, v77
	v_cvt_pk_bf16_f32 v118, v108, v109
	v_cvt_pk_bf16_f32 v119, v110, v111
	v_cvt_pk_bf16_f32 v120, v72, v73
	v_cvt_pk_bf16_f32 v121, v80, v81
	v_cvt_pk_bf16_f32 v122, v112, v113
	v_cvt_pk_bf16_f32 v123, v114, v115
	ds_write_b128 v124, v[116:119] offset:17408
	ds_write_b128 v125, v[120:123] offset:17408
	v_cmp_gt_i32_e32 vcc, s49, v157
	s_and_saveexec_b64 s[0:1], vcc
	v_lshl_add_u32 v2, v157, 2, 0
	v_add_u32_e32 v2, 0x18500, v2
	ds_write_b32 v2, v158
	s_or_b64 exec, exec, s[0:1]
	v_ashrrev_i32_e32 v91, 6, v157
	v_ashrrev_i32_e32 v76, 7, v157
	v_and_b32_e32 v88, 15, v157
	v_lshlrev_b32_e32 v2, 1, v91
	v_lshlrev_b32_e32 v73, 4, v76
	v_and_b32_e32 v3, 48, v161
	v_and_b32_e32 v77, 2, v2
	v_or_b32_e32 v2, v73, v88
	v_add_u32_e32 v72, 0, v3
	v_mad_u64_u32 v[2:3], s[0:1], v2, s48, v[72:73]
	v_cmp_gt_i32_e64 s[14:15], v77, v76
	v_cmp_le_i32_e32 vcc, v77, v76
	v_lshl_or_b32 v80, v77, 4, v88
	v_mov_b32_e32 v68, 0
	v_mov_b32_e32 v69, 0
	v_mov_b32_e32 v70, 0
	v_mov_b32_e32 v71, 0
	s_waitcnt lgkmcnt(0)
	s_barrier
	s_and_saveexec_b64 s[0:1], vcc
	s_cbranch_execz .LBB0_725
	ds_read_b128 v[68:71], v2
	v_mad_u32_u24 v3, v80, s48, v72
	ds_read_b128 v[82:85], v2 offset:64
	ds_read_b128 v[92:95], v3 offset:17408
	ds_read_b128 v[96:99], v3 offset:17472
	s_waitcnt lgkmcnt(1)
	v_mfma_f32_16x16x32_bf16 v[68:71], v[68:71], v[92:95], 0
	ds_read_b128 v[92:95], v2 offset:128
	ds_read_b128 v[100:103], v2 offset:192
	s_waitcnt lgkmcnt(2)
	v_mfma_f32_16x16x32_bf16 v[68:71], v[82:85], v[96:99], v[68:71]
	ds_read_b128 v[82:85], v3 offset:17536
	ds_read_b128 v[96:99], v3 offset:17600
	s_waitcnt lgkmcnt(1)
	v_mfma_f32_16x16x32_bf16 v[68:71], v[92:95], v[82:85], v[68:71]
	s_waitcnt lgkmcnt(0)
	v_mfma_f32_16x16x32_bf16 v[68:71], v[100:103], v[96:99], v[68:71]
